# P1: odd workgroups run GEMM1 first and convert their share of the weights afterwards (even ones convert first, as before), so the HBM-bound conversion overlaps the other half's GEMM
# speedup vs baseline: 1.0096x; 1.0019x over previous
_Z3fwd4Args:
	v_writelane_b32 v249, s0, 0
	v_writelane_b32 v249, s1, 1
	v_writelane_b32 v249, s2, 2
	v_mov_b32_e32 v250, v0
	s_and_b32 s101, s2, 1
	s_lshl_b32 s101, s101, 8
.Lcls_top:
	s_load_dword s95, s[0:1], 0xf0
	v_lshrrev_b32_e32 v160, 6, v0
	s_mov_b64 s[96:97], s[0:1]
	v_readfirstlane_b32 s0, v160
	s_mov_b32 s84, s2
	s_nop 0
	v_writelane_b32 v248, s0, 0
	s_add_u32 s0, s96, 0xf0
	s_addc_u32 s1, s97, 0
	v_writelane_b32 v248, s0, 1
	s_nop 1
	v_writelane_b32 v248, s1, 2
	s_waitcnt lgkmcnt(0)
	s_and_b32 s0, s95, 7
	s_cmp_lg_u32 s0, 0
	v_writelane_b32 v248, s84, 3
	s_cbranch_scc1 .LBB0_2
	s_ashr_i32 s1, s84, 31
	s_lshr_b32 s1, s1, 29
	s_add_i32 s1, s84, s1
	s_and_b32 s2, s1, -8
	s_ashr_i32 s0, s95, 3
	s_sub_i32 s2, s84, s2
	s_mul_i32 s0, s0, s2
	s_ashr_i32 s1, s1, 3
	s_add_i32 s0, s0, s1
	v_writelane_b32 v248, s0, 3
.LBB0_2:
	s_load_dwordx2 s[8:9], s[96:97], 0xe8
	s_load_dwordx4 s[4:7], s[96:97], 0xd8
	v_cmp_gt_u32_e32 vcc, 64, v0
	s_and_saveexec_b64 s[0:1], vcc
	s_and_b32 s98, s101, 0xff
	s_cmp_lg_u32 s98, 0
	s_cbranch_scc1 .Lcls_nozero
	v_lshl_add_u32 v1, v0, 2, 0
	v_add_u32_e32 v1, 0x23f00, v1
	v_mov_b32_e32 v2, 0
	ds_write_b32 v1, v2
.Lcls_nozero:
	s_waitcnt lgkmcnt(0)
	s_and_b32 s98, s101, 0xff
	s_max_u32 s8, s8, s98
	v_writelane_b32 v248, s8, 4
	s_nop 1
	v_writelane_b32 v248, s9, 5
	s_or_b64 exec, exec, s[0:1]
	s_add_u32 s0, s6, 0x1000
	v_writelane_b32 v248, s4, 6
	s_addc_u32 s1, s7, 0
	s_nop 0
	v_writelane_b32 v248, s5, 7
	v_writelane_b32 v248, s6, 8
	v_writelane_b32 v248, s7, 9
	v_writelane_b32 v248, s0, 10
	s_barrier
	s_nop 0
	v_writelane_b32 v248, s1, 11
	s_getreg_b32 s0, hwreg(HW_REG_XCC_ID, 0, 4)
	s_and_b32 s0, s0, 15
	v_writelane_b32 v248, s0, 12
	v_cmp_eq_u32_e64 s[2:3], 0, v0
	s_mov_b64 s[0:1], exec
	s_nop 0
	v_writelane_b32 v248, s2, 13
	s_nop 1
	v_writelane_b32 v248, s3, 14
	s_and_b64 s[2:3], s[0:1], s[2:3]
	s_mov_b64 exec, s[2:3]
	s_cbranch_execz .LBB0_7
	s_mov_b64 s[2:3], exec
	v_mbcnt_lo_u32_b32 v1, s2, 0
	v_mbcnt_hi_u32_b32 v1, s3, v1
	v_cmp_eq_u32_e32 vcc, 0, v1
	s_and_b64 s[4:5], exec, vcc
	s_mov_b64 exec, s[4:5]
	s_cbranch_execz .LBB0_7
	s_and_b32 s98, s101, 0xff
	s_cmp_lg_u32 s98, 0
	s_cbranch_scc1 .LBB0_7
	v_readlane_b32 s4, v248, 12
	s_bcnt1_i32_b64 s2, s[2:3]
	s_lshl_b32 s4, s4, 8
	v_mov_b32_e32 v2, s2
	v_readlane_b32 s2, v248, 10
	v_mov_b32_e32 v1, s4
	v_readlane_b32 s3, v248, 11
	s_nop 4
	global_atomic_add v1, v2, s[2:3] offset:1024
.LBB0_7:
	s_or_b64 exec, exec, s[0:1]
	v_readlane_b32 s0, v248, 3
	s_lshl_b32 s1, s0, 3
	v_readlane_b32 s0, v248, 0
	v_writelane_b32 v248, s1, 15
	s_add_i32 s66, s1, s0
	s_load_dwordx4 s[0:3], s[96:97], 0xd8
	s_load_dwordx2 s[4:5], s[96:97], 0xe8
	s_lshl_b32 s59, s95, 3
	v_and_b32_e32 v206, 63, v0
	s_waitcnt lgkmcnt(0)
	s_and_b32 s98, s101, 0xff
	s_max_u32 s4, s4, s98
	s_add_u32 s0, s2, 0x100000
	s_addc_u32 s1, s3, 0
	s_add_u32 s24, s2, 0x140000
	v_writelane_b32 v248, s0, 16
	s_addc_u32 s25, s3, 0
	s_nop 0
	v_writelane_b32 v248, s1, 17
	s_add_u32 s0, s2, 0x800000
	s_addc_u32 s1, s3, 0
	v_writelane_b32 v248, s0, 18
	s_nop 1
	v_writelane_b32 v248, s1, 19
	s_add_u32 s0, s2, 0x1da00000
	s_addc_u32 s1, s3, 0
	v_writelane_b32 v248, s0, 20
	s_nop 1
	v_writelane_b32 v248, s1, 21
	s_add_u32 s0, s2, 0x31e00000
	s_addc_u32 s1, s3, 0
	v_writelane_b32 v248, s0, 22
	s_nop 1
	v_writelane_b32 v248, s1, 23
	s_add_u32 s0, s2, 0x4800000
	s_addc_u32 s1, s3, 0
	v_writelane_b32 v248, s0, 24
	s_nop 1
	v_writelane_b32 v248, s1, 25
	s_add_u32 s0, s2, 0x320000
	s_addc_u32 s1, s3, 0
	v_writelane_b32 v248, s0, 26
	s_nop 1
	v_writelane_b32 v248, s1, 27
	s_add_u32 s0, s2, 0x560000
	s_addc_u32 s1, s3, 0
	v_writelane_b32 v248, s0, 28
	s_cmp_lt_i32 s4, 1
	s_nop 0
	v_writelane_b32 v248, s1, 29
	s_cselect_b64 s[0:1], -1, 0
	s_cmp_gt_i32 s5, 0
	s_cselect_b64 s[2:3], -1, 0
	s_and_b64 s[0:1], s[0:1], s[2:3]
	s_andn2_b64 vcc, exec, s[0:1]
	s_mov_b32 s0, s66
	v_writelane_b32 v248, s0, 30
	s_nop 1
	v_writelane_b32 v248, s1, 31
	v_writelane_b32 v248, s84, 32
	s_cbranch_vccnz .LBB0_189
	s_mov_b64 s[0:1], s[96:97]
	s_load_dwordx2 s[0:1], s[0:1], 0x0
	s_mov_b64 s[2:3], s[96:97]
	s_mov_b64 s[4:5], s[96:97]
	s_mov_b64 s[6:7], s[96:97]
	s_mov_b64 s[8:9], s[96:97]
	s_waitcnt lgkmcnt(0)
	v_writelane_b32 v248, s0, 33
	s_mov_b64 s[10:11], s[96:97]
	s_mov_b64 s[12:13], s[96:97]
	v_writelane_b32 v248, s1, 34
	s_mov_b64 s[0:1], s[96:97]
	s_load_dwordx2 s[0:1], s[0:1], 0x8
	s_mov_b64 s[14:15], s[96:97]
	s_mov_b64 s[16:17], s[96:97]
	s_mov_b64 s[68:69], s[96:97]
	s_cmpk_gt_i32 s84, 0x7f
	s_waitcnt lgkmcnt(0)
	v_writelane_b32 v248, s0, 35
	s_nop 1
	v_writelane_b32 v248, s1, 36
	s_mov_b64 s[0:1], s[96:97]
	s_load_dwordx2 s[0:1], s[0:1], 0x28
	s_waitcnt lgkmcnt(0)
	v_writelane_b32 v248, s0, 37
	s_nop 1
	v_writelane_b32 v248, s1, 38
	s_mov_b64 s[0:1], s[96:97]
	s_load_dwordx2 s[0:1], s[0:1], 0x30
	s_waitcnt lgkmcnt(0)
	v_writelane_b32 v248, s0, 39
	s_nop 1
	v_writelane_b32 v248, s1, 40
	s_mov_b64 s[0:1], s[96:97]
	s_load_dwordx2 s[0:1], s[0:1], 0x38
	s_waitcnt lgkmcnt(0)
	v_writelane_b32 v248, s0, 41
	s_nop 1
	v_writelane_b32 v248, s1, 42
	s_mov_b64 s[0:1], s[96:97]
	s_mov_b64 s[16:17], s[96:97]
	s_mov_b64 s[16:17], s[96:97]
	s_mov_b64 s[16:17], s[96:97]
	s_mov_b64 s[16:17], s[96:97]
	s_mov_b64 s[16:17], s[96:97]
	s_cbranch_scc1 .LBB0_100
	s_load_dwordx2 s[0:1], s[0:1], 0x40
	v_lshlrev_b32_e32 v2, 4, v0
	v_and_b32_e32 v3, 0xf00, v2
	v_and_b32_e32 v84, 15, v0
	v_add_u32_e32 v3, 0, v3
	s_waitcnt lgkmcnt(0)
	v_writelane_b32 v248, s0, 43
	v_bfe_u32 v87, v0, 4, 1
	v_add_u32_e32 v93, 0x3200, v3
	v_writelane_b32 v248, s1, 44
	s_load_dwordx2 s[0:1], s[2:3], 0x48
	v_lshl_add_u32 v3, v84, 2, 0
	v_add_u32_e32 v94, 0x1200, v3
	v_sub_u32_e32 v3, v87, v160
	v_mov_b32_e32 v18, 0
	s_waitcnt lgkmcnt(0)
	v_writelane_b32 v248, s0, 45
	v_add_u32_e32 v95, 32, v3
	v_mov_b32_e32 v3, 0xfffffcc0
	v_writelane_b32 v248, s1, 46
	s_load_dwordx2 s[60:61], s[4:5], 0x50
	s_load_dwordx2 s[0:1], s[6:7], 0x58
	v_and_b32_e32 v4, 0x1c0, v0
	s_load_dword s6, s[68:69], 0xf0
	v_lshl_add_u32 v96, v160, 4, v3
	v_mov_b32_e32 v3, v18
	s_waitcnt lgkmcnt(0)
	v_writelane_b32 v248, s0, 47
	v_add_u32_e32 v82, 0xffffff80, v0
	s_lshl_b32 s47, s6, 10
	v_writelane_b32 v248, s1, 48
	s_load_dwordx2 s[0:1], s[8:9], 0x60
	v_lshl_add_u32 v83, v0, 2, 0
	s_mul_hi_i32 s73, s6, 0x15000
	s_mul_i32 s72, s6, 0x15000
	s_mov_b32 s74, 0x652b82fe
	s_waitcnt lgkmcnt(0)
	v_writelane_b32 v248, s0, 49
	s_mov_b32 s76, 0xfefa39ef
	s_mov_b32 s78, 0x3b39803f
	v_writelane_b32 v248, s1, 50
	s_load_dwordx2 s[0:1], s[10:11], 0x68
	s_mov_b32 s80, 0x6a5dcb37
	s_mov_b32 s82, 0x11110bb3
	s_mov_b32 s54, 0x55555555
	s_mov_b32 s38, 0x54442d18
	s_waitcnt lgkmcnt(0)
	v_writelane_b32 v248, s0, 51
	s_mov_b32 s88, 0x6dc9c883
	s_mov_b32 s26, 0x33145c00
	v_writelane_b32 v248, s1, 52
	s_load_dwordx2 s[0:1], s[12:13], 0x70
	s_mov_b32 s92, 0x252049c0
	s_mov_b32 s94, 0x9037ab78
	s_mov_b32 s96, 0x46cc5e42
	s_mov_b32 s42, 0xa17f65f6
	s_waitcnt lgkmcnt(0)
	v_writelane_b32 v248, s0, 53
	s_mov_b32 s12, 0x19f4ec90
	s_mov_b32 s40, 0x16c16967
	v_writelane_b32 v248, s1, 54
	s_load_dwordx2 s[0:1], s[14:15], 0x78
	s_mov_b32 s52, 0xb42fdfa7
	s_mov_b32 s36, 0xf9a43bb8
	s_mov_b32 s30, 0x796cde01
	s_mov_b32 s48, 0x19e83e5c
	s_waitcnt lgkmcnt(0)
	v_writelane_b32 v248, s0, 55
	s_mov_b32 s50, 0
	s_mov_b32 s22, 0
	v_writelane_b32 v248, s1, 56
	s_movk_i32 s0, 0x280
	v_readlane_b32 s14, v248, 32
	v_readlane_b32 s8, v248, 6
	s_mul_i32 s2, s14, 0x15000
	v_readlane_b32 s10, v248, 8
	s_mul_hi_i32 s1, s14, 0x15000
	v_readlane_b32 s11, v248, 9
	s_add_u32 s2, s10, s2
	v_cmp_gt_u32_e64 s[4:5], s0, v0
	s_movk_i32 s0, 0x80
	s_addc_u32 s3, s11, s1
	v_readlane_b32 s9, v248, 7
	v_lshl_add_u64 v[2:3], s[2:3], 0, v[2:3]
	s_mov_b64 s[2:3], 0x36600000
	v_cmp_eq_u32_e64 s[6:7], s0, v4
	s_mov_b32 s0, 0
	s_mov_b32 s28, 0
	s_mov_b32 s44, 0
	s_movk_i32 s46, 0xff80
	v_and_b32_e32 v85, 31, v0
	v_lshl_add_u32 v86, v82, 6, 0
	v_lshl_add_u32 v88, v84, 6, 0
	v_mul_i32_i24_e32 v89, 0xffffffc4, v84
	v_mov_b32_e32 v1, v18
	v_add_u32_e32 v90, 0x3200, v83
	v_or_b32_e32 v91, 0xfffffe00, v0
	v_lshl_or_b32 v20, s14, 10, v0
	v_lshrrev_b32_e32 v92, 8, v0
	v_lshl_add_u64 v[22:23], v[2:3], 0, s[2:3]
	s_mov_b32 s75, 0x3ff71547
	s_mov_b32 s77, 0xbfe62e42
	s_mov_b32 s79, 0xbc7abc9e
	v_mov_b32_e32 v24, 0xfca7ab0c
	v_mov_b32_e32 v25, 0x3e928af3
	s_mov_b32 s81, 0x3e5ade15
	v_mov_b32_e32 v26, 0x623fde64
	v_mov_b32_e32 v27, 0x3ec71dee
	v_mov_b32_e32 v28, 0x7c89e6b0
	v_mov_b32_e32 v29, 0x3efa0199
	v_mov_b32_e32 v30, 0x14761f6e
	v_mov_b32_e32 v31, 0x3f2a01a0
	v_mov_b32_e32 v32, 0x1852b7b0
	v_mov_b32_e32 v33, 0x3f56c16c
	s_mov_b32 s83, 0x3f811111
	v_mov_b32_e32 v34, 0x11122322
	v_mov_b32_e32 v35, 0x3f811111
	s_mov_b32 s55, 0x3fa55555
	v_mov_b32_e32 v36, 0x555502a1
	v_mov_b32_e32 v37, 0x3fa55555
	v_mov_b32_e32 v38, 0x55555511
	v_mov_b32_e32 v39, 0x3fc55555
	v_mov_b32_e32 v40, 11
	v_mov_b32_e32 v41, 0x3fe00000
	s_mov_b32 s39, 0xbff921fb
	s_mov_b32 s89, 0x3fe45f30
	s_mov_b32 s27, 0xbc91a626
	s_mov_b32 s93, 0xb97b839a
	s_mov_b32 s95, 0x3e21eeb6
	s_mov_b32 s97, 0xbda907db
	s_mov_b32 s43, 0xbe927e4f
	s_mov_b32 s13, 0x3efa01a0
	s_mov_b32 s41, 0xbf56c16c
	s_mov_b32 s53, 0xbe5ae600
	s_mov_b32 s37, 0x3de5e0b2
	s_mov_b32 s31, 0x3ec71de3
	s_mov_b32 s49, 0xbf2a01a0
	s_brev_b32 s33, 1
	s_movk_i32 s56, 0x1f8
	v_mov_b32_e32 v42, 0x2a1b768b
	v_mov_b32_e32 v44, 0xe0ac05b
	v_mov_b32_e32 v46, 0x1b889c29
	v_mov_b32_e32 v48, 0x197bcfd8
	v_mov_b32_e32 v50, 0x1ac1a723
	v_mov_b32_e32 v52, 0x16c18931
	v_mov_b32_e32 v54, 0x11110056
	v_mov_b32_e32 v56, 0x55555552
	v_mov_b32_e32 v58, 0x55555557
	v_lshlrev_b32_e32 v97, 6, v0
	v_lshrrev_b32_e32 v98, 4, v0
	v_subrev_u32_e32 v99, 52, v160
	v_lshrrev_b32_e32 v100, 2, v0
	v_mov_b32_e32 v101, 0x7ff00000
	v_mov_b32_e32 v102, 0x40700000
	v_mov_b32_e32 v103, 0x40100000
	v_mov_b32_e32 v104, 0x3ff00000
	v_mov_b32_e32 v105, 0x7ff80000
	s_movk_i32 s57, 0x7fff
	v_mov_b32_e32 v106, 0x7fe00000
	s_mov_b32 s58, 0xffff0000
	v_mov_b32_e32 v107, 0xbff00000
	v_mov_b32_e32 v43, 0x3e5af4eb
	v_mov_b32_e32 v45, 0x3e927e50
	v_mov_b32_e32 v47, 0x3ec71de0
	v_mov_b32_e32 v49, 0x3efa01a0
	v_cmp_gt_u32_e64 s[8:9], 16, v0
	s_mov_b32 s1, 0x41d00000
	s_mov_b32 s51, 0x7b000000
	s_mov_b32 s23, 0x7ff00000
	s_mov_b32 s87, 0x3ff921fb
	s_mov_b32 s91, 0x3c91a626
	s_mov_b32 s20, 0x33145c07
	s_mov_b32 s29, 0x40900000
	s_mov_b32 s45, 0xc090cc00
	s_mov_b32 s85, 0xbfc55555
	s_mov_b32 s35, 0x40862e42
	s_mov_b64 s[16:17], 0x800
	s_mov_b32 s18, s14
	s_branch .LBB0_11

.LBB0_189:
	v_writelane_b32 v248, s59, 41
	s_nop 0
	v_readlane_b32 s0, v248, 6
	v_readlane_b32 s2, v248, 8
	v_readlane_b32 s1, v248, 7
	v_readlane_b32 s3, v248, 9
	s_add_u32 s0, s2, 0x240000
	s_addc_u32 s1, s3, 0
	v_writelane_b32 v248, s0, 55
	s_nop 1
	v_writelane_b32 v248, s1, 56
	s_add_u32 s0, s2, 0x2c0000
	s_addc_u32 s1, s3, 0
	s_add_u32 s60, s2, 0x8800000
	s_addc_u32 s61, s3, 0
	s_add_u32 s30, s2, 0xa800000
	s_addc_u32 s31, s3, 0
	s_add_u32 s82, s2, 0xb800000
	v_writelane_b32 v248, s0, 43
	s_addc_u32 s83, s3, 0
	s_nop 0
	v_writelane_b32 v248, s1, 44
	s_add_u32 s0, s2, 0x18400000
	v_writelane_b32 v248, s0, 33
	s_addc_u32 s0, s3, 0
	s_add_u32 s14, s2, 0x22200000
	s_addc_u32 s15, s3, 0
	v_writelane_b32 v248, s0, 47
	s_add_u32 s0, s2, 0x24600000
	s_addc_u32 s1, s3, 0
	v_writelane_b32 v248, s0, 45
	s_nop 1
	v_writelane_b32 v248, s1, 46
	s_add_u32 s0, s2, 0x26a00000
	s_addc_u32 s1, s3, 0
	s_add_u32 s56, s2, 0x28e00000
	s_addc_u32 s57, s3, 0
	s_add_u32 s58, s2, 0x2d600000
	s_addc_u32 s59, s3, 0
	s_add_u32 s48, s2, 0x540000
	v_writelane_b32 v248, s0, 49
	s_addc_u32 s49, s3, 0
	s_nop 0
	v_writelane_b32 v248, s1, 50
	s_add_u32 s0, s2, 0xd800000
	v_writelane_b32 v248, s0, 51
	s_addc_u32 s0, s3, 0
	s_cmp_lt_i32 s4, 2
	v_writelane_b32 v248, s0, 53
	s_cselect_b64 s[0:1], -1, 0
	s_cmp_gt_i32 s5, 1
	s_cselect_b64 s[2:3], -1, 0
	s_and_b64 s[0:1], s[0:1], s[2:3]
	s_andn2_b64 vcc, exec, s[0:1]
	v_writelane_b32 v248, s82, 37
	s_nop 1
	v_writelane_b32 v248, s83, 38
	s_cbranch_vccnz .LBB0_380
	s_bitcmp1_b32 s101, 10
	s_cbranch_scc0 .Lcls_nobaronly
	s_and_b32 s101, s101, 0xff
	s_branch .LBB0_326
.Lcls_nobaronly:
	s_bitcmp1_b32 s101, 8
	s_cbranch_scc0 .Lcls_docopy
	v_writelane_b32 v248, s96, 59
	v_writelane_b32 v248, s97, 60
	v_lshlrev_b32_e32 v1, 2, v0
	v_and_b32_e32 v130, 48, v0
	s_branch .LBB0_222
.Lcls_docopy:
	v_readlane_b32 s6, v248, 3
	s_mov_b64 s[4:5], s[96:97]
	s_mov_b64 s[8:9], s[96:97]
	s_mov_b64 s[10:11], s[96:97]
	s_mov_b64 s[12:13], s[96:97]
	s_mov_b64 s[0:1], s[96:97]
	s_mov_b64 s[2:3], s[96:97]
	s_mov_b64 s[16:17], s[96:97]
	s_cmpk_lt_i32 s6, 0x2b0
	s_cbranch_scc1 .LBB0_192
	v_readlane_b32 s6, v248, 0
	s_lshl_b32 s21, s6, 14
	v_lshlrev_b32_e32 v1, 2, v0
	s_mov_b64 s[18:19], 0
	s_branch .LBB0_193

.LBB0_222:
	s_bitcmp1_b32 s101, 9
	s_cbranch_scc0 .Lcls_nocopyonly
	s_mov_b64 exec, -1
	s_movk_i32 s101, 0x401
	v_readlane_b32 s0, v249, 0
	v_readlane_b32 s1, v249, 1
	v_readlane_b32 s2, v249, 2
	v_mov_b32_e32 v0, v250
	s_nop 4
	s_branch .Lcls_top

.LBB0_326:
	s_bitcmp1_b32 s101, 8
	s_cbranch_scc0 .Lcls_noreenter
	s_mov_b64 exec, -1
	s_movk_i32 s101, 0x201
	v_readlane_b32 s0, v249, 0
	v_readlane_b32 s1, v249, 1
	v_readlane_b32 s2, v249, 2
	v_mov_b32_e32 v0, v250
	s_nop 4
	s_branch .Lcls_top

	.amdhsa_kernel _Z3fwd4Args
		.amdhsa_group_segment_fixed_size 0
		.amdhsa_private_segment_fixed_size 0
		.amdhsa_kernarg_size 496
		.amdhsa_user_sgpr_count 2
		.amdhsa_user_sgpr_dispatch_ptr 0
		.amdhsa_user_sgpr_queue_ptr 0
		.amdhsa_user_sgpr_kernarg_segment_ptr 1
		.amdhsa_user_sgpr_dispatch_id 0
		.amdhsa_user_sgpr_kernarg_preload_length 0
		.amdhsa_user_sgpr_kernarg_preload_offset 0
		.amdhsa_user_sgpr_private_segment_size 0
		.amdhsa_uses_dynamic_stack 0
		.amdhsa_enable_private_segment 0
		.amdhsa_system_sgpr_workgroup_id_x 1
		.amdhsa_system_sgpr_workgroup_id_y 0
		.amdhsa_system_sgpr_workgroup_id_z 0
		.amdhsa_system_sgpr_workgroup_info 0
		.amdhsa_system_vgpr_workitem_id 0
		.amdhsa_next_free_vgpr 251
		.amdhsa_next_free_sgpr 102
		.amdhsa_accum_offset 252
		.amdhsa_reserve_vcc 1
		.amdhsa_float_round_mode_32 0
		.amdhsa_float_round_mode_16_64 0
		.amdhsa_float_denorm_mode_32 3
		.amdhsa_float_denorm_mode_16_64 3
		.amdhsa_dx10_clamp 1
		.amdhsa_ieee_mode 1
		.amdhsa_fp16_overflow 0
		.amdhsa_tg_split 0
		.amdhsa_exception_fp_ieee_invalid_op 0
		.amdhsa_exception_fp_denorm_src 0
		.amdhsa_exception_fp_ieee_div_zero 0
		.amdhsa_exception_fp_ieee_overflow 0
		.amdhsa_exception_fp_ieee_underflow 0
		.amdhsa_exception_fp_ieee_inexact 0
		.amdhsa_exception_int_div_zero 0
	.end_amdhsa_kernel

amdhsa.kernels:
  - .agpr_count:     0
    .args:
      - .offset:         0
        .size:           240
        .value_kind:     by_value
      - .offset:         240
        .size:           4
        .value_kind:     hidden_block_count_x
      - .offset:         244
        .size:           4
        .value_kind:     hidden_block_count_y
      - .offset:         248
        .size:           4
        .value_kind:     hidden_block_count_z
      - .offset:         252
        .size:           2
        .value_kind:     hidden_group_size_x
      - .offset:         254
        .size:           2
        .value_kind:     hidden_group_size_y
      - .offset:         256
        .size:           2
        .value_kind:     hidden_group_size_z
      - .offset:         258
        .size:           2
        .value_kind:     hidden_remainder_x
      - .offset:         260
        .size:           2
        .value_kind:     hidden_remainder_y
      - .offset:         262
        .size:           2
        .value_kind:     hidden_remainder_z
      - .offset:         280
        .size:           8
        .value_kind:     hidden_global_offset_x
      - .offset:         288
        .size:           8
        .value_kind:     hidden_global_offset_y
      - .offset:         296
        .size:           8
        .value_kind:     hidden_global_offset_z
      - .offset:         304
        .size:           2
        .value_kind:     hidden_grid_dims
      - .offset:         360
        .size:           4
        .value_kind:     hidden_dynamic_lds_size
    .group_segment_fixed_size: 0
    .kernarg_segment_align: 8
    .kernarg_segment_size: 496
    .language:       OpenCL C
    .language_version:
      - 2
      - 0
    .max_flat_workgroup_size: 512
    .name:           _Z3fwd4Args
    .private_segment_fixed_size: 0
    .sgpr_count:     108
    .sgpr_spill_count: 81
    .symbol:         _Z3fwd4Args.kd
    .uniform_work_group_size: 1
    .uses_dynamic_stack: false
    .vgpr_count:     251
    .vgpr_spill_count: 0
    .wavefront_size: 64
